# final_norm: write-back (non-streaming) stores instead of nt so the loop-top wait is not held by streaming store acks
# baseline (speedup 1.0000x reference)
.LBB0_2642:
	s_or_b64 exec, exec, s[0:1]
	v_add_u32_e32 v32, s8, v59
	v_cmp_lt_i32_e32 vcc, s10, v32
	v_lshl_add_u64 v[0:1], v[38:39], 0, v[42:43]
	s_or_b64 s[4:5], vcc, s[4:5]
	global_store_dwordx4 v[0:1], v[12:15], off offset:3072
	s_andn2_b64 exec, exec, s[4:5]
	s_cbranch_execz .LBB0_2651
.LBB0_2643:
	v_ashrrev_i32_e32 v33, 31, v32
	v_lshlrev_b64 v[46:47], 12, v[32:33]
	v_add_u32_e32 v59, s8, v32
	v_lshl_add_u64 v[44:45], v[38:39], 0, v[46:47]
	v_cmp_gt_i32_e32 vcc, s7, v59
	global_load_dwordx4 v[60:63], v[44:45], off nt
	global_load_dwordx4 v[16:19], v[44:45], off offset:1024 nt
	global_load_dwordx4 v[0:3], v[44:45], off offset:3072 nt
	global_load_dwordx4 v[12:15], v[44:45], off offset:2048 nt
	v_cndmask_b32_e32 v34, v32, v59, vcc
	v_ashrrev_i32_e32 v35, 31, v34
	v_lshlrev_b64 v[42:43], 12, v[34:35]
	v_lshl_add_u64 v[48:49], v[38:39], 0, v[42:43]
	global_load_dwordx4 v[24:27], v[48:49], off nt
	global_load_dwordx4 v[20:23], v[48:49], off offset:1024 nt
	global_load_dwordx4 v[4:7], v[48:49], off offset:3072 nt
	global_load_dwordx4 v[8:11], v[48:49], off offset:2048 nt
	global_load_dwordx4 v[28:31], v[36:37], off
	v_cmp_ne_u32_e32 vcc, v32, v34
	s_waitcnt vmcnt(0)
	v_pk_mul_f32 v[50:51], v[62:63], v[62:63]
	v_pk_mul_f32 v[52:53], v[60:61], v[60:61]
	v_pk_mul_f32 v[64:65], v[18:19], v[18:19]
	v_pk_mul_f32 v[66:67], v[16:17], v[16:17]
	v_mul_f32_e32 v68, v13, v13
	v_mul_f32_e32 v70, v15, v15
	v_pk_mov_b32 v[72:73], v[52:53], v[50:51] op_sel:[1,0]
	v_mov_b32_e32 v53, v51
	v_pk_mov_b32 v[50:51], v[66:67], v[64:65] op_sel:[1,0]
	v_mov_b32_e32 v67, v65
	v_pk_fma_f32 v[64:65], v[12:13], v[12:13], v[68:69] op_sel_hi:[1,1,0]
	v_pk_fma_f32 v[68:69], v[14:15], v[14:15], v[70:71] op_sel_hi:[1,1,0]
	v_pk_add_f32 v[52:53], v[72:73], v[52:53]
	v_pk_mul_f32 v[70:71], v[26:27], v[26:27]
	v_pk_mul_f32 v[72:73], v[24:25], v[24:25]
	v_pk_add_f32 v[50:51], v[50:51], v[66:67]
	v_pk_mul_f32 v[66:67], v[22:23], v[22:23]
	v_pk_mul_f32 v[74:75], v[20:21], v[20:21]
	v_mul_f32_e32 v33, v0, v0
	v_mul_f32_e32 v35, v1, v1
	v_mul_f32_e32 v76, v2, v2
	v_mul_f32_e32 v77, v3, v3
	v_pk_mov_b32 v[80:81], v[72:73], v[70:71] op_sel:[1,0]
	v_mov_b32_e32 v73, v71
	v_pk_mov_b32 v[70:71], v[74:75], v[66:67] op_sel:[1,0]
	v_mov_b32_e32 v75, v67
	v_pk_add_f32 v[52:53], v[52:53], v[52:53] op_sel:[0,1] op_sel_hi:[1,0]
	v_pk_add_f32 v[50:51], v[50:51], v[50:51] op_sel:[0,1] op_sel_hi:[1,0]
	v_mov_b32_e32 v65, v76
	v_mov_b32_e32 v69, v77
	v_mul_f32_e32 v77, v4, v4
	v_mul_f32_e32 v79, v5, v5
	v_mul_f32_e32 v76, v9, v9
	v_mul_f32_e32 v78, v11, v11
	v_pk_add_f32 v[72:73], v[80:81], v[72:73]
	v_pk_add_f32 v[70:71], v[70:71], v[74:75]
	v_mov_b32_e32 v53, v33
	v_mov_b32_e32 v51, v35
	v_mul_f32_e32 v82, v6, v6
	v_mul_f32_e32 v83, v7, v7
	v_pk_add_f32 v[64:65], v[64:65], v[68:69]
	v_pk_fma_f32 v[66:67], v[8:9], v[8:9], v[76:77] op_sel_hi:[1,1,0]
	v_pk_fma_f32 v[68:69], v[10:11], v[10:11], v[78:79] op_sel_hi:[1,1,0]
	v_pk_add_f32 v[50:51], v[52:53], v[50:51]
	v_pk_add_f32 v[52:53], v[72:73], v[72:73] op_sel:[0,1] op_sel_hi:[1,0]
	v_pk_add_f32 v[70:71], v[70:71], v[70:71] op_sel:[0,1] op_sel_hi:[1,0]
	v_mov_b32_e32 v67, v82
	v_mov_b32_e32 v69, v83
	v_mov_b32_e32 v53, v77
	v_mov_b32_e32 v71, v79
	v_pk_add_f32 v[66:67], v[66:67], v[68:69]
	v_pk_add_f32 v[52:53], v[52:53], v[70:71]
	v_pk_add_f32 v[50:51], v[50:51], v[64:65]
	v_pk_add_f32 v[52:53], v[52:53], v[66:67]
	v_mov_b32_e32 v65, v50
	v_mov_b32_e32 v64, v52
	v_mov_b32_e32 v50, v53
	v_pk_add_f32 v[50:51], v[64:65], v[50:51]
	global_load_dwordx4 v[84:87], v[36:37], off offset:1024
	global_load_dwordx4 v[88:91], v[36:37], off offset:1024
	global_load_dwordx4 v[92:95], v[36:37], off offset:2048
	global_load_dwordx4 v[96:99], v[36:37], off offset:3072
	global_load_dwordx4 v[100:103], v[36:37], off offset:3072
	ds_bpermute_b32 v53, v41, v51
	ds_bpermute_b32 v52, v41, v50
	s_waitcnt lgkmcnt(0)
	v_pk_add_f32 v[50:51], v[50:51], v[52:53]
	ds_bpermute_b32 v53, v54, v51
	ds_bpermute_b32 v52, v54, v50
	s_waitcnt lgkmcnt(0)
	v_pk_add_f32 v[50:51], v[50:51], v[52:53]
	ds_bpermute_b32 v53, v55, v51
	ds_bpermute_b32 v52, v55, v50
	s_waitcnt lgkmcnt(0)
	v_pk_add_f32 v[50:51], v[50:51], v[52:53]
	ds_bpermute_b32 v53, v56, v51
	ds_bpermute_b32 v52, v56, v50
	s_waitcnt lgkmcnt(0)
	v_pk_add_f32 v[50:51], v[50:51], v[52:53]
	ds_bpermute_b32 v53, v57, v51
	ds_bpermute_b32 v52, v57, v50
	s_waitcnt lgkmcnt(0)
	v_pk_add_f32 v[50:51], v[50:51], v[52:53]
	ds_bpermute_b32 v53, v58, v51
	ds_bpermute_b32 v52, v58, v50
	s_waitcnt lgkmcnt(0)
	s_waitcnt vmcnt(0)
	v_pk_add_f32 v[50:51], v[50:51], v[52:53]
	s_nop 0
	v_pk_fma_f32 v[50:51], v[50:51], s[6:7], v[40:41] op_sel_hi:[1,0,0]
	s_nop 0
	v_mul_f32_e32 v33, 0x4b800000, v51
	v_cmp_gt_f32_e64 s[0:1], s9, v51
	v_mul_f32_e32 v35, 0x4b800000, v50
	v_cmp_gt_f32_e64 s[2:3], s9, v50
	v_cndmask_b32_e64 v33, v51, v33, s[0:1]
	v_rsq_f32_e32 v33, v33
	v_cndmask_b32_e64 v35, v50, v35, s[2:3]
	v_rsq_f32_e32 v35, v35
	v_mul_f32_e32 v32, 0x45800000, v33
	v_cndmask_b32_e64 v52, v33, v32, s[0:1]
	v_mul_f32_e32 v34, 0x45800000, v35
	v_mov_b32_e32 v53, v52
	v_cndmask_b32_e64 v50, v35, v34, s[2:3]
	v_pk_mul_f32 v[32:33], v[60:61], v[52:53] op_sel_hi:[1,0]
	v_pk_mul_f32 v[34:35], v[62:63], v[52:53] op_sel_hi:[1,0]
	v_mov_b32_e32 v51, v50
	v_pk_mul_f32 v[34:35], v[30:31], v[34:35]
	v_pk_mul_f32 v[32:33], v[28:29], v[32:33]
	v_pk_mul_f32 v[16:17], v[16:17], v[52:53]
	global_store_dwordx4 v[44:45], v[32:35], off
	s_and_saveexec_b64 s[0:1], vcc
	s_xor_b64 s[0:1], exec, s[0:1]
	s_cbranch_execz .LBB0_2645
	v_mov_b32_e32 v32, v50
	v_mov_b32_e32 v33, v50
	v_pk_mul_f32 v[26:27], v[26:27], v[32:33]
	v_pk_mul_f32 v[24:25], v[24:25], v[50:51]
	v_pk_mul_f32 v[26:27], v[30:31], v[26:27]
	v_pk_mul_f32 v[24:25], v[28:29], v[24:25]
	global_store_dwordx4 v[48:49], v[24:27], off
	s_nop 1
	v_mov_b64_e32 v[24:25], v[84:85]
	v_mov_b64_e32 v[26:27], v[86:87]
	v_mov_b32_e32 v28, v52
	v_mov_b32_e32 v29, v52
	v_pk_mul_f32 v[18:19], v[18:19], v[28:29]
	v_pk_mul_f32 v[20:21], v[20:21], v[50:51]
	v_pk_mul_f32 v[22:23], v[22:23], v[32:33]
	s_nop 0
	v_pk_mul_f32 v[18:19], v[18:19], v[26:27]
	v_pk_mul_f32 v[16:17], v[16:17], v[24:25]
	v_pk_mul_f32 v[34:35], v[22:23], v[26:27]
	global_store_dwordx4 v[44:45], v[16:19], off offset:1024
	v_pk_mul_f32 v[32:33], v[20:21], v[24:25]

.LBB0_2647:
	s_or_b64 exec, exec, s[0:1]
	v_lshl_add_u64 v[16:17], v[38:39], 0, v[20:21]
	global_store_dwordx4 v[16:17], v[32:35], off offset:1024
	v_mov_b64_e32 v[16:17], v[92:93]
	v_mov_b64_e32 v[18:19], v[94:95]
	v_mov_b32_e32 v20, v52
	v_mov_b32_e32 v21, v52
	v_pk_mul_f32 v[12:13], v[12:13], v[52:53]
	v_pk_mul_f32 v[14:15], v[14:15], v[20:21]
	v_pk_mul_f32 v[0:1], v[0:1], v[52:53]
	s_nop 0
	v_pk_mul_f32 v[14:15], v[14:15], v[18:19]
	v_pk_mul_f32 v[12:13], v[12:13], v[16:17]
	global_store_dwordx4 v[44:45], v[12:15], off offset:2048
	s_and_saveexec_b64 s[0:1], vcc
	s_xor_b64 s[0:1], exec, s[0:1]
	s_cbranch_execz .LBB0_2649
	v_mov_b32_e32 v12, v50
	v_mov_b32_e32 v13, v50
	v_pk_mul_f32 v[10:11], v[10:11], v[12:13]
	v_pk_mul_f32 v[8:9], v[8:9], v[50:51]
	v_pk_mul_f32 v[10:11], v[10:11], v[18:19]
	v_pk_mul_f32 v[8:9], v[8:9], v[16:17]
	global_store_dwordx4 v[48:49], v[8:11], off offset:2048
	s_nop 1
	v_mov_b64_e32 v[8:9], v[96:97]
	v_mov_b64_e32 v[10:11], v[98:99]
	v_pk_mul_f32 v[2:3], v[2:3], v[20:21]
	v_pk_mul_f32 v[4:5], v[4:5], v[50:51]
	v_pk_mul_f32 v[6:7], v[6:7], v[12:13]
	s_nop 0
	v_pk_mul_f32 v[2:3], v[2:3], v[10:11]
	v_pk_mul_f32 v[0:1], v[0:1], v[8:9]
	v_pk_mul_f32 v[14:15], v[6:7], v[10:11]
	global_store_dwordx4 v[44:45], v[0:3], off offset:3072
	v_pk_mul_f32 v[12:13], v[4:5], v[8:9]
